# straight-line first-stage residual epilogue (layer 0 FFN-a out, raw f32 input rows): 16 serialized HBM round trips per unit replaced by loads issued ahead of the stores; on top of v043
# speedup vs baseline: 1.0119x; 1.0119x over previous
.Lxfast:
	s_waitcnt lgkmcnt(0)
	s_cmp_lt_i32 s4, 32
	s_cselect_b32 s6, 0, 0xffffe000
	s_cselect_b32 s1, s56, s58
	s_cselect_b32 s0, s43, s57
	v_add_u32_e32 v187, s6, v180
	v_lshlrev_b32_e32 v187, 13, v187
	v_lshl_add_u32 v187, v178, 2, v187
	v_lshlrev_b32_e32 v226, 12, v180
	v_lshl_add_u32 v226, v178, 1, v226
	v_lshl_add_u32 v227, v191, 4, v180
	v_lshlrev_b32_e32 v227, 3, v227
	v_cmp_lt_i32_e32 vcc, v234, v230
	s_nop 1
	v_cndmask_b32_e32 v201, v228, v234, vcc
	v_cmp_lt_i32_e32 vcc, v195, v230
	s_nop 1
	v_cndmask_b32_e32 v203, v228, v195, vcc
	v_lshlrev_b32_e32 v201, 2, v201
	v_lshlrev_b32_e32 v203, 2, v203
	global_load_dwordx4 v[204:207], v187, s[0:1]
	global_load_dwordx4 v[142:145], v187, s[0:1] offset:16
	v_add_u32_e32 v197, 0x20000, v187
	global_load_dwordx4 v[208:211], v197, s[0:1]
	global_load_dwordx4 v[146:149], v197, s[0:1] offset:16
	v_add_u32_e32 v199, 0x40000, v187
	global_load_dwordx4 v[212:215], v199, s[0:1]
	global_load_dwordx4 v[150:153], v199, s[0:1] offset:16
	v_add_u32_e32 v197, 0x60000, v187
	global_load_dwordx4 v[216:219], v197, s[0:1]
	global_load_dwordx4 v[154:157], v197, s[0:1] offset:16
	global_load_dwordx4 v[158:161], v187, s[0:1] offset:512
	global_load_dwordx4 v[174:177], v187, s[0:1] offset:528
	v_add_u32_e32 v199, 0x20000, v187
	global_load_dwordx4 v[162:165], v199, s[0:1] offset:512
	global_load_dwordx4 v[178:181], v199, s[0:1] offset:528
	v_add_u32_e32 v197, 0x40000, v187
	global_load_dwordx4 v[166:169], v197, s[0:1] offset:512
	global_load_dwordx4 v[182:185], v197, s[0:1] offset:528
	v_add_u32_e32 v199, 0x60000, v187
	global_load_dwordx4 v[170:173], v199, s[0:1] offset:512
	global_load_dwordx4 v[222:225], v199, s[0:1] offset:528
	s_waitcnt vmcnt(8)
	v_pk_mul_f32 v[204:205], v[204:205], s[76:77] op_sel_hi:[1,0]
	v_pk_mul_f32 v[206:207], v[206:207], s[76:77] op_sel_hi:[1,0]
	v_pk_mul_f32 v[142:143], v[142:143], s[76:77] op_sel_hi:[1,0]
	v_pk_mul_f32 v[144:145], v[144:145], s[76:77] op_sel_hi:[1,0]
	v_pk_fma_f32 v[126:127], v[126:127], 0.5, v[204:205] op_sel_hi:[1,0,1]
	v_pk_fma_f32 v[128:129], v[128:129], 0.5, v[206:207] op_sel_hi:[1,0,1]
	v_pk_fma_f32 v[130:131], v[130:131], 0.5, v[142:143] op_sel_hi:[1,0,1]
	v_pk_fma_f32 v[132:133], v[132:133], 0.5, v[144:145] op_sel_hi:[1,0,1]
	v_pk_add_f32 v[204:205], v[126:127], v[130:131]
	v_pk_add_f32 v[206:207], v[128:129], v[132:133]
	v_pk_mul_f32 v[142:143], v[126:127], v[126:127]
	v_pk_mul_f32 v[144:145], v[128:129], v[128:129]
	v_pk_fma_f32 v[142:143], v[130:131], v[130:131], v[142:143]
	v_pk_fma_f32 v[144:145], v[132:133], v[132:133], v[144:145]
	v_pk_add_f32 v[204:205], v[204:205], v[206:207]
	v_pk_add_f32 v[142:143], v[142:143], v[144:145]
	v_add_f32_e32 v2, v204, v205
	v_add_f32_e32 v139, v142, v143
	v_cvt_pk_bf16_f32 v204, v126, v127
	v_cvt_pk_bf16_f32 v205, v128, v129
	v_cvt_pk_bf16_f32 v206, v130, v131
	v_cvt_pk_bf16_f32 v207, v132, v133
	v_pk_mul_f32 v[208:209], v[208:209], s[76:77] op_sel_hi:[1,0]
	v_pk_mul_f32 v[210:211], v[210:211], s[76:77] op_sel_hi:[1,0]
	v_pk_mul_f32 v[146:147], v[146:147], s[76:77] op_sel_hi:[1,0]
	v_pk_mul_f32 v[148:149], v[148:149], s[76:77] op_sel_hi:[1,0]
	v_pk_fma_f32 v[118:119], v[118:119], 0.5, v[208:209] op_sel_hi:[1,0,1]
	v_pk_fma_f32 v[120:121], v[120:121], 0.5, v[210:211] op_sel_hi:[1,0,1]
	v_pk_fma_f32 v[122:123], v[122:123], 0.5, v[146:147] op_sel_hi:[1,0,1]
	v_pk_fma_f32 v[124:125], v[124:125], 0.5, v[148:149] op_sel_hi:[1,0,1]
	v_pk_add_f32 v[208:209], v[118:119], v[122:123]
	v_pk_add_f32 v[210:211], v[120:121], v[124:125]
	v_pk_mul_f32 v[146:147], v[118:119], v[118:119]
	v_pk_mul_f32 v[148:149], v[120:121], v[120:121]
	v_pk_fma_f32 v[146:147], v[122:123], v[122:123], v[146:147]
	v_pk_fma_f32 v[148:149], v[124:125], v[124:125], v[148:149]
	v_pk_add_f32 v[208:209], v[208:209], v[210:211]
	v_pk_add_f32 v[146:147], v[146:147], v[148:149]
	v_add_f32_e32 v4, v208, v209
	v_add_f32_e32 v140, v146, v147
	v_cvt_pk_bf16_f32 v208, v118, v119
	v_cvt_pk_bf16_f32 v209, v120, v121
	v_cvt_pk_bf16_f32 v210, v122, v123
	v_cvt_pk_bf16_f32 v211, v124, v125
	v_pk_mul_f32 v[212:213], v[212:213], s[76:77] op_sel_hi:[1,0]
	v_pk_mul_f32 v[214:215], v[214:215], s[76:77] op_sel_hi:[1,0]
	v_pk_mul_f32 v[150:151], v[150:151], s[76:77] op_sel_hi:[1,0]
	v_pk_mul_f32 v[152:153], v[152:153], s[76:77] op_sel_hi:[1,0]
	v_pk_fma_f32 v[110:111], v[110:111], 0.5, v[212:213] op_sel_hi:[1,0,1]
	v_pk_fma_f32 v[112:113], v[112:113], 0.5, v[214:215] op_sel_hi:[1,0,1]
	v_pk_fma_f32 v[114:115], v[114:115], 0.5, v[150:151] op_sel_hi:[1,0,1]
	v_pk_fma_f32 v[116:117], v[116:117], 0.5, v[152:153] op_sel_hi:[1,0,1]
	v_pk_add_f32 v[212:213], v[110:111], v[114:115]
	v_pk_add_f32 v[214:215], v[112:113], v[116:117]
	v_pk_mul_f32 v[150:151], v[110:111], v[110:111]
	v_pk_mul_f32 v[152:153], v[112:113], v[112:113]
	v_pk_fma_f32 v[150:151], v[114:115], v[114:115], v[150:151]
	v_pk_fma_f32 v[152:153], v[116:117], v[116:117], v[152:153]
	v_pk_add_f32 v[212:213], v[212:213], v[214:215]
	v_pk_add_f32 v[150:151], v[150:151], v[152:153]
	v_add_f32_e32 v5, v212, v213
	v_add_f32_e32 v141, v150, v151
	v_cvt_pk_bf16_f32 v212, v110, v111
	v_cvt_pk_bf16_f32 v213, v112, v113
	v_cvt_pk_bf16_f32 v214, v114, v115
	v_cvt_pk_bf16_f32 v215, v116, v117
	v_pk_mul_f32 v[216:217], v[216:217], s[76:77] op_sel_hi:[1,0]
	v_pk_mul_f32 v[218:219], v[218:219], s[76:77] op_sel_hi:[1,0]
	v_pk_mul_f32 v[154:155], v[154:155], s[76:77] op_sel_hi:[1,0]
	v_pk_mul_f32 v[156:157], v[156:157], s[76:77] op_sel_hi:[1,0]
	v_pk_fma_f32 v[102:103], v[102:103], 0.5, v[216:217] op_sel_hi:[1,0,1]
	v_pk_fma_f32 v[104:105], v[104:105], 0.5, v[218:219] op_sel_hi:[1,0,1]
	v_pk_fma_f32 v[106:107], v[106:107], 0.5, v[154:155] op_sel_hi:[1,0,1]
	v_pk_fma_f32 v[108:109], v[108:109], 0.5, v[156:157] op_sel_hi:[1,0,1]
	v_pk_add_f32 v[216:217], v[102:103], v[106:107]
	v_pk_add_f32 v[218:219], v[104:105], v[108:109]
	v_pk_mul_f32 v[154:155], v[102:103], v[102:103]
	v_pk_mul_f32 v[156:157], v[104:105], v[104:105]
	v_pk_fma_f32 v[154:155], v[106:107], v[106:107], v[154:155]
	v_pk_fma_f32 v[156:157], v[108:109], v[108:109], v[156:157]
	v_pk_add_f32 v[216:217], v[216:217], v[218:219]
	v_pk_add_f32 v[154:155], v[154:155], v[156:157]
	v_add_f32_e32 v138, v216, v217
	v_add_f32_e32 v186, v154, v155
	v_cvt_pk_bf16_f32 v216, v102, v103
	v_cvt_pk_bf16_f32 v217, v104, v105
	v_cvt_pk_bf16_f32 v218, v106, v107
	v_cvt_pk_bf16_f32 v219, v108, v109
	v_add_u32_e32 v197, 0x100000, v187
	global_load_dwordx4 v[102:105], v197, s[0:1]
	global_load_dwordx4 v[118:121], v197, s[0:1] offset:16
	v_add_u32_e32 v199, 0x120000, v187
	global_load_dwordx4 v[106:109], v199, s[0:1]
	global_load_dwordx4 v[122:125], v199, s[0:1] offset:16
	v_add_u32_e32 v197, 0x140000, v187
	global_load_dwordx4 v[110:113], v197, s[0:1]
	global_load_dwordx4 v[126:129], v197, s[0:1] offset:16
	v_add_u32_e32 v199, 0x160000, v187
	global_load_dwordx4 v[114:117], v199, s[0:1]
	global_load_dwordx4 v[130:133], v199, s[0:1] offset:16
	global_store_dwordx4 v226, v[204:207], s[18:19]
	v_add_u32_e32 v197, 0x10000, v226
	global_store_dwordx4 v197, v[208:211], s[18:19]
	v_add_u32_e32 v199, 0x20000, v226
	global_store_dwordx4 v199, v[212:215], s[18:19]
	v_add_u32_e32 v197, 0x30000, v226
	global_store_dwordx4 v197, v[216:219], s[18:19]
	s_waitcnt vmcnt(12)
	v_pk_mul_f32 v[158:159], v[158:159], s[76:77] op_sel_hi:[1,0]
	v_pk_mul_f32 v[160:161], v[160:161], s[76:77] op_sel_hi:[1,0]
	v_pk_mul_f32 v[174:175], v[174:175], s[76:77] op_sel_hi:[1,0]
	v_pk_mul_f32 v[176:177], v[176:177], s[76:77] op_sel_hi:[1,0]
	v_pk_fma_f32 v[94:95], v[94:95], 0.5, v[158:159] op_sel_hi:[1,0,1]
	v_pk_fma_f32 v[96:97], v[96:97], 0.5, v[160:161] op_sel_hi:[1,0,1]
	v_pk_fma_f32 v[98:99], v[98:99], 0.5, v[174:175] op_sel_hi:[1,0,1]
	v_pk_fma_f32 v[100:101], v[100:101], 0.5, v[176:177] op_sel_hi:[1,0,1]
	v_pk_add_f32 v[158:159], v[94:95], v[98:99]
	v_pk_add_f32 v[160:161], v[96:97], v[100:101]
	v_pk_mul_f32 v[174:175], v[94:95], v[94:95]
	v_pk_mul_f32 v[176:177], v[96:97], v[96:97]
	v_pk_fma_f32 v[174:175], v[98:99], v[98:99], v[174:175]
	v_pk_fma_f32 v[176:177], v[100:101], v[100:101], v[176:177]
	v_pk_add_f32 v[158:159], v[158:159], v[160:161]
	v_pk_add_f32 v[174:175], v[174:175], v[176:177]
	v_add_f32_e32 v158, v158, v159
	v_add_f32_e32 v174, v174, v175
	v_add_f32_e32 v2, v2, v158
	v_add_f32_e32 v139, v139, v174
	v_cvt_pk_bf16_f32 v158, v94, v95
	v_cvt_pk_bf16_f32 v159, v96, v97
	v_cvt_pk_bf16_f32 v160, v98, v99
	v_cvt_pk_bf16_f32 v161, v100, v101
	v_pk_mul_f32 v[162:163], v[162:163], s[76:77] op_sel_hi:[1,0]
	v_pk_mul_f32 v[164:165], v[164:165], s[76:77] op_sel_hi:[1,0]
	v_pk_mul_f32 v[178:179], v[178:179], s[76:77] op_sel_hi:[1,0]
	v_pk_mul_f32 v[180:181], v[180:181], s[76:77] op_sel_hi:[1,0]
	v_pk_fma_f32 v[86:87], v[86:87], 0.5, v[162:163] op_sel_hi:[1,0,1]
	v_pk_fma_f32 v[88:89], v[88:89], 0.5, v[164:165] op_sel_hi:[1,0,1]
	v_pk_fma_f32 v[90:91], v[90:91], 0.5, v[178:179] op_sel_hi:[1,0,1]
	v_pk_fma_f32 v[92:93], v[92:93], 0.5, v[180:181] op_sel_hi:[1,0,1]
	v_pk_add_f32 v[162:163], v[86:87], v[90:91]
	v_pk_add_f32 v[164:165], v[88:89], v[92:93]
	v_pk_mul_f32 v[178:179], v[86:87], v[86:87]
	v_pk_mul_f32 v[180:181], v[88:89], v[88:89]
	v_pk_fma_f32 v[178:179], v[90:91], v[90:91], v[178:179]
	v_pk_fma_f32 v[180:181], v[92:93], v[92:93], v[180:181]
	v_pk_add_f32 v[162:163], v[162:163], v[164:165]
	v_pk_add_f32 v[178:179], v[178:179], v[180:181]
	v_add_f32_e32 v162, v162, v163
	v_add_f32_e32 v178, v178, v179
	v_add_f32_e32 v4, v4, v162
	v_add_f32_e32 v140, v140, v178
	v_cvt_pk_bf16_f32 v162, v86, v87
	v_cvt_pk_bf16_f32 v163, v88, v89
	v_cvt_pk_bf16_f32 v164, v90, v91
	v_cvt_pk_bf16_f32 v165, v92, v93
	v_pk_mul_f32 v[166:167], v[166:167], s[76:77] op_sel_hi:[1,0]
	v_pk_mul_f32 v[168:169], v[168:169], s[76:77] op_sel_hi:[1,0]
	v_pk_mul_f32 v[182:183], v[182:183], s[76:77] op_sel_hi:[1,0]
	v_pk_mul_f32 v[184:185], v[184:185], s[76:77] op_sel_hi:[1,0]
	v_pk_fma_f32 v[78:79], v[78:79], 0.5, v[166:167] op_sel_hi:[1,0,1]
	v_pk_fma_f32 v[80:81], v[80:81], 0.5, v[168:169] op_sel_hi:[1,0,1]
	v_pk_fma_f32 v[82:83], v[82:83], 0.5, v[182:183] op_sel_hi:[1,0,1]
	v_pk_fma_f32 v[84:85], v[84:85], 0.5, v[184:185] op_sel_hi:[1,0,1]
	v_pk_add_f32 v[166:167], v[78:79], v[82:83]
	v_pk_add_f32 v[168:169], v[80:81], v[84:85]
	v_pk_mul_f32 v[182:183], v[78:79], v[78:79]
	v_pk_mul_f32 v[184:185], v[80:81], v[80:81]
	v_pk_fma_f32 v[182:183], v[82:83], v[82:83], v[182:183]
	v_pk_fma_f32 v[184:185], v[84:85], v[84:85], v[184:185]
	v_pk_add_f32 v[166:167], v[166:167], v[168:169]
	v_pk_add_f32 v[182:183], v[182:183], v[184:185]
	v_add_f32_e32 v166, v166, v167
	v_add_f32_e32 v182, v182, v183
	v_add_f32_e32 v5, v5, v166
	v_add_f32_e32 v141, v141, v182
	v_cvt_pk_bf16_f32 v166, v78, v79
	v_cvt_pk_bf16_f32 v167, v80, v81
	v_cvt_pk_bf16_f32 v168, v82, v83
	v_cvt_pk_bf16_f32 v169, v84, v85
	v_pk_mul_f32 v[170:171], v[170:171], s[76:77] op_sel_hi:[1,0]
	v_pk_mul_f32 v[172:173], v[172:173], s[76:77] op_sel_hi:[1,0]
	v_pk_mul_f32 v[222:223], v[222:223], s[76:77] op_sel_hi:[1,0]
	v_pk_mul_f32 v[224:225], v[224:225], s[76:77] op_sel_hi:[1,0]
	v_pk_fma_f32 v[70:71], v[70:71], 0.5, v[170:171] op_sel_hi:[1,0,1]
	v_pk_fma_f32 v[72:73], v[72:73], 0.5, v[172:173] op_sel_hi:[1,0,1]
	v_pk_fma_f32 v[74:75], v[74:75], 0.5, v[222:223] op_sel_hi:[1,0,1]
	v_pk_fma_f32 v[76:77], v[76:77], 0.5, v[224:225] op_sel_hi:[1,0,1]
	v_pk_add_f32 v[170:171], v[70:71], v[74:75]
	v_pk_add_f32 v[172:173], v[72:73], v[76:77]
	v_pk_mul_f32 v[222:223], v[70:71], v[70:71]
	v_pk_mul_f32 v[224:225], v[72:73], v[72:73]
	v_pk_fma_f32 v[222:223], v[74:75], v[74:75], v[222:223]
	v_pk_fma_f32 v[224:225], v[76:77], v[76:77], v[224:225]
	v_pk_add_f32 v[170:171], v[170:171], v[172:173]
	v_pk_add_f32 v[222:223], v[222:223], v[224:225]
	v_add_f32_e32 v170, v170, v171
	v_add_f32_e32 v222, v222, v223
	v_add_f32_e32 v138, v138, v170
	v_add_f32_e32 v186, v186, v222
	v_cvt_pk_bf16_f32 v170, v70, v71
	v_cvt_pk_bf16_f32 v171, v72, v73
	v_cvt_pk_bf16_f32 v172, v74, v75
	v_cvt_pk_bf16_f32 v173, v76, v77
	v_add_u32_e32 v199, 0x100000, v187
	global_load_dwordx4 v[70:73], v199, s[0:1] offset:512
	global_load_dwordx4 v[86:89], v199, s[0:1] offset:528
	v_add_u32_e32 v197, 0x120000, v187
	global_load_dwordx4 v[74:77], v197, s[0:1] offset:512
	global_load_dwordx4 v[90:93], v197, s[0:1] offset:528
	v_add_u32_e32 v199, 0x140000, v187
	global_load_dwordx4 v[78:81], v199, s[0:1] offset:512
	global_load_dwordx4 v[94:97], v199, s[0:1] offset:528
	v_add_u32_e32 v197, 0x160000, v187
	global_load_dwordx4 v[82:85], v197, s[0:1] offset:512
	global_load_dwordx4 v[98:101], v197, s[0:1] offset:528
	global_store_dwordx4 v226, v[158:161], s[18:19] offset:256
	v_add_u32_e32 v199, 0x10000, v226
	global_store_dwordx4 v199, v[162:165], s[18:19] offset:256
	v_add_u32_e32 v197, 0x20000, v226
	global_store_dwordx4 v197, v[166:169], s[18:19] offset:256
	v_add_u32_e32 v199, 0x30000, v226
	global_store_dwordx4 v199, v[170:173], s[18:19] offset:256
	ds_bpermute_b32 v134, v201, v2
	ds_bpermute_b32 v135, v201, v4
	ds_bpermute_b32 v136, v201, v5
	ds_bpermute_b32 v137, v201, v138
	ds_bpermute_b32 v222, v201, v139
	ds_bpermute_b32 v223, v201, v140
	ds_bpermute_b32 v224, v201, v141
	ds_bpermute_b32 v225, v201, v186
	s_waitcnt lgkmcnt(0)
	v_add_f32_e32 v2, v2, v134
	v_add_f32_e32 v4, v4, v135
	v_add_f32_e32 v5, v5, v136
	v_add_f32_e32 v138, v138, v137
	v_add_f32_e32 v139, v139, v222
	v_add_f32_e32 v140, v140, v223
	v_add_f32_e32 v141, v141, v224
	v_add_f32_e32 v186, v186, v225
	ds_bpermute_b32 v134, v203, v2
	ds_bpermute_b32 v135, v203, v4
	ds_bpermute_b32 v136, v203, v5
	ds_bpermute_b32 v137, v203, v138
	ds_bpermute_b32 v222, v203, v139
	ds_bpermute_b32 v223, v203, v140
	ds_bpermute_b32 v224, v203, v141
	ds_bpermute_b32 v225, v203, v186
	s_waitcnt lgkmcnt(0)
	v_add_f32_e32 v2, v2, v134
	v_add_f32_e32 v4, v4, v135
	v_add_f32_e32 v5, v5, v136
	v_add_f32_e32 v138, v138, v137
	v_add_f32_e32 v139, v139, v222
	v_add_f32_e32 v140, v140, v223
	v_add_f32_e32 v141, v141, v224
	v_add_f32_e32 v186, v186, v225
	v_cmp_eq_u32_e32 vcc, 1, v191
	s_nop 1
	v_cndmask_b32_e32 v2, v2, v4, vcc
	v_cndmask_b32_e32 v139, v139, v140, vcc
	v_cmp_eq_u32_e32 vcc, 2, v191
	s_nop 1
	v_cndmask_b32_e32 v2, v2, v5, vcc
	v_cndmask_b32_e32 v139, v139, v141, vcc
	v_cmp_eq_u32_e32 vcc, 3, v191
	s_nop 1
	v_cndmask_b32_e32 v2, v2, v138, vcc
	v_cndmask_b32_e32 v139, v139, v186, vcc
	global_atomic_add_f32 v227, v2, s[16:17]
	global_atomic_add_f32 v227, v139, s[16:17] offset:4
	s_waitcnt vmcnt(18)
	v_pk_mul_f32 v[102:103], v[102:103], s[76:77] op_sel_hi:[1,0]
	v_pk_mul_f32 v[104:105], v[104:105], s[76:77] op_sel_hi:[1,0]
	v_pk_mul_f32 v[118:119], v[118:119], s[76:77] op_sel_hi:[1,0]
	v_pk_mul_f32 v[120:121], v[120:121], s[76:77] op_sel_hi:[1,0]
	v_pk_fma_f32 v[46:47], v[46:47], 0.5, v[102:103] op_sel_hi:[1,0,1]
	v_pk_fma_f32 v[48:49], v[48:49], 0.5, v[104:105] op_sel_hi:[1,0,1]
	v_pk_fma_f32 v[50:51], v[50:51], 0.5, v[118:119] op_sel_hi:[1,0,1]
	v_pk_fma_f32 v[52:53], v[52:53], 0.5, v[120:121] op_sel_hi:[1,0,1]
	v_pk_add_f32 v[102:103], v[46:47], v[50:51]
	v_pk_add_f32 v[104:105], v[48:49], v[52:53]
	v_pk_mul_f32 v[118:119], v[46:47], v[46:47]
	v_pk_mul_f32 v[120:121], v[48:49], v[48:49]
	v_pk_fma_f32 v[118:119], v[50:51], v[50:51], v[118:119]
	v_pk_fma_f32 v[120:121], v[52:53], v[52:53], v[120:121]
	v_pk_add_f32 v[102:103], v[102:103], v[104:105]
	v_pk_add_f32 v[118:119], v[118:119], v[120:121]
	v_add_f32_e32 v2, v102, v103
	v_add_f32_e32 v139, v118, v119
	v_cvt_pk_bf16_f32 v102, v46, v47
	v_cvt_pk_bf16_f32 v103, v48, v49
	v_cvt_pk_bf16_f32 v104, v50, v51
	v_cvt_pk_bf16_f32 v105, v52, v53
	v_pk_mul_f32 v[106:107], v[106:107], s[76:77] op_sel_hi:[1,0]
	v_pk_mul_f32 v[108:109], v[108:109], s[76:77] op_sel_hi:[1,0]
	v_pk_mul_f32 v[122:123], v[122:123], s[76:77] op_sel_hi:[1,0]
	v_pk_mul_f32 v[124:125], v[124:125], s[76:77] op_sel_hi:[1,0]
	v_pk_fma_f32 v[38:39], v[38:39], 0.5, v[106:107] op_sel_hi:[1,0,1]
	v_pk_fma_f32 v[40:41], v[40:41], 0.5, v[108:109] op_sel_hi:[1,0,1]
	v_pk_fma_f32 v[42:43], v[42:43], 0.5, v[122:123] op_sel_hi:[1,0,1]
	v_pk_fma_f32 v[44:45], v[44:45], 0.5, v[124:125] op_sel_hi:[1,0,1]
	v_pk_add_f32 v[106:107], v[38:39], v[42:43]
	v_pk_add_f32 v[108:109], v[40:41], v[44:45]
	v_pk_mul_f32 v[122:123], v[38:39], v[38:39]
	v_pk_mul_f32 v[124:125], v[40:41], v[40:41]
	v_pk_fma_f32 v[122:123], v[42:43], v[42:43], v[122:123]
	v_pk_fma_f32 v[124:125], v[44:45], v[44:45], v[124:125]
	v_pk_add_f32 v[106:107], v[106:107], v[108:109]
	v_pk_add_f32 v[122:123], v[122:123], v[124:125]
	v_add_f32_e32 v4, v106, v107
	v_add_f32_e32 v140, v122, v123
	v_cvt_pk_bf16_f32 v106, v38, v39
	v_cvt_pk_bf16_f32 v107, v40, v41
	v_cvt_pk_bf16_f32 v108, v42, v43
	v_cvt_pk_bf16_f32 v109, v44, v45
	v_pk_mul_f32 v[110:111], v[110:111], s[76:77] op_sel_hi:[1,0]
	v_pk_mul_f32 v[112:113], v[112:113], s[76:77] op_sel_hi:[1,0]
	v_pk_mul_f32 v[126:127], v[126:127], s[76:77] op_sel_hi:[1,0]
	v_pk_mul_f32 v[128:129], v[128:129], s[76:77] op_sel_hi:[1,0]
	v_pk_fma_f32 v[30:31], v[30:31], 0.5, v[110:111] op_sel_hi:[1,0,1]
	v_pk_fma_f32 v[32:33], v[32:33], 0.5, v[112:113] op_sel_hi:[1,0,1]
	v_pk_fma_f32 v[34:35], v[34:35], 0.5, v[126:127] op_sel_hi:[1,0,1]
	v_pk_fma_f32 v[36:37], v[36:37], 0.5, v[128:129] op_sel_hi:[1,0,1]
	v_pk_add_f32 v[110:111], v[30:31], v[34:35]
	v_pk_add_f32 v[112:113], v[32:33], v[36:37]
	v_pk_mul_f32 v[126:127], v[30:31], v[30:31]
	v_pk_mul_f32 v[128:129], v[32:33], v[32:33]
	v_pk_fma_f32 v[126:127], v[34:35], v[34:35], v[126:127]
	v_pk_fma_f32 v[128:129], v[36:37], v[36:37], v[128:129]
	v_pk_add_f32 v[110:111], v[110:111], v[112:113]
	v_pk_add_f32 v[126:127], v[126:127], v[128:129]
	v_add_f32_e32 v5, v110, v111
	v_add_f32_e32 v141, v126, v127
	v_cvt_pk_bf16_f32 v110, v30, v31
	v_cvt_pk_bf16_f32 v111, v32, v33
	v_cvt_pk_bf16_f32 v112, v34, v35
	v_cvt_pk_bf16_f32 v113, v36, v37
	v_pk_mul_f32 v[114:115], v[114:115], s[76:77] op_sel_hi:[1,0]
	v_pk_mul_f32 v[116:117], v[116:117], s[76:77] op_sel_hi:[1,0]
	v_pk_mul_f32 v[130:131], v[130:131], s[76:77] op_sel_hi:[1,0]
	v_pk_mul_f32 v[132:133], v[132:133], s[76:77] op_sel_hi:[1,0]
	v_pk_fma_f32 v[22:23], v[22:23], 0.5, v[114:115] op_sel_hi:[1,0,1]
	v_pk_fma_f32 v[24:25], v[24:25], 0.5, v[116:117] op_sel_hi:[1,0,1]
	v_pk_fma_f32 v[26:27], v[26:27], 0.5, v[130:131] op_sel_hi:[1,0,1]
	v_pk_fma_f32 v[28:29], v[28:29], 0.5, v[132:133] op_sel_hi:[1,0,1]
	v_pk_add_f32 v[114:115], v[22:23], v[26:27]
	v_pk_add_f32 v[116:117], v[24:25], v[28:29]
	v_pk_mul_f32 v[130:131], v[22:23], v[22:23]
	v_pk_mul_f32 v[132:133], v[24:25], v[24:25]
	v_pk_fma_f32 v[130:131], v[26:27], v[26:27], v[130:131]
	v_pk_fma_f32 v[132:133], v[28:29], v[28:29], v[132:133]
	v_pk_add_f32 v[114:115], v[114:115], v[116:117]
	v_pk_add_f32 v[130:131], v[130:131], v[132:133]
	v_add_f32_e32 v138, v114, v115
	v_add_f32_e32 v186, v130, v131
	v_cvt_pk_bf16_f32 v114, v22, v23
	v_cvt_pk_bf16_f32 v115, v24, v25
	v_cvt_pk_bf16_f32 v116, v26, v27
	v_cvt_pk_bf16_f32 v117, v28, v29
	v_add_u32_e32 v197, 0x80000, v226
	global_store_dwordx4 v197, v[102:105], s[18:19]
	v_add_u32_e32 v199, 0x90000, v226
	global_store_dwordx4 v199, v[106:109], s[18:19]
	v_add_u32_e32 v197, 0xa0000, v226
	global_store_dwordx4 v197, v[110:113], s[18:19]
	v_add_u32_e32 v199, 0xb0000, v226
	global_store_dwordx4 v199, v[114:117], s[18:19]
	s_waitcnt vmcnt(10)
	v_pk_mul_f32 v[70:71], v[70:71], s[76:77] op_sel_hi:[1,0]
	v_pk_mul_f32 v[72:73], v[72:73], s[76:77] op_sel_hi:[1,0]
	v_pk_mul_f32 v[86:87], v[86:87], s[76:77] op_sel_hi:[1,0]
	v_pk_mul_f32 v[88:89], v[88:89], s[76:77] op_sel_hi:[1,0]
	v_pk_fma_f32 v[14:15], v[14:15], 0.5, v[70:71] op_sel_hi:[1,0,1]
	v_pk_fma_f32 v[16:17], v[16:17], 0.5, v[72:73] op_sel_hi:[1,0,1]
	v_pk_fma_f32 v[18:19], v[18:19], 0.5, v[86:87] op_sel_hi:[1,0,1]
	v_pk_fma_f32 v[20:21], v[20:21], 0.5, v[88:89] op_sel_hi:[1,0,1]
	v_pk_add_f32 v[70:71], v[14:15], v[18:19]
	v_pk_add_f32 v[72:73], v[16:17], v[20:21]
	v_pk_mul_f32 v[86:87], v[14:15], v[14:15]
	v_pk_mul_f32 v[88:89], v[16:17], v[16:17]
	v_pk_fma_f32 v[86:87], v[18:19], v[18:19], v[86:87]
	v_pk_fma_f32 v[88:89], v[20:21], v[20:21], v[88:89]
	v_pk_add_f32 v[70:71], v[70:71], v[72:73]
	v_pk_add_f32 v[86:87], v[86:87], v[88:89]
	v_add_f32_e32 v70, v70, v71
	v_add_f32_e32 v86, v86, v87
	v_add_f32_e32 v2, v2, v70
	v_add_f32_e32 v139, v139, v86
	v_cvt_pk_bf16_f32 v70, v14, v15
	v_cvt_pk_bf16_f32 v71, v16, v17
	v_cvt_pk_bf16_f32 v72, v18, v19
	v_cvt_pk_bf16_f32 v73, v20, v21
	v_pk_mul_f32 v[74:75], v[74:75], s[76:77] op_sel_hi:[1,0]
	v_pk_mul_f32 v[76:77], v[76:77], s[76:77] op_sel_hi:[1,0]
	v_pk_mul_f32 v[90:91], v[90:91], s[76:77] op_sel_hi:[1,0]
	v_pk_mul_f32 v[92:93], v[92:93], s[76:77] op_sel_hi:[1,0]
	v_pk_fma_f32 v[6:7], v[6:7], 0.5, v[74:75] op_sel_hi:[1,0,1]
	v_pk_fma_f32 v[8:9], v[8:9], 0.5, v[76:77] op_sel_hi:[1,0,1]
	v_pk_fma_f32 v[10:11], v[10:11], 0.5, v[90:91] op_sel_hi:[1,0,1]
	v_pk_fma_f32 v[12:13], v[12:13], 0.5, v[92:93] op_sel_hi:[1,0,1]
	v_pk_add_f32 v[74:75], v[6:7], v[10:11]
	v_pk_add_f32 v[76:77], v[8:9], v[12:13]
	v_pk_mul_f32 v[90:91], v[6:7], v[6:7]
	v_pk_mul_f32 v[92:93], v[8:9], v[8:9]
	v_pk_fma_f32 v[90:91], v[10:11], v[10:11], v[90:91]
	v_pk_fma_f32 v[92:93], v[12:13], v[12:13], v[92:93]
	v_pk_add_f32 v[74:75], v[74:75], v[76:77]
	v_pk_add_f32 v[90:91], v[90:91], v[92:93]
	v_add_f32_e32 v74, v74, v75
	v_add_f32_e32 v90, v90, v91
	v_add_f32_e32 v4, v4, v74
	v_add_f32_e32 v140, v140, v90
	v_cvt_pk_bf16_f32 v74, v6, v7
	v_cvt_pk_bf16_f32 v75, v8, v9
	v_cvt_pk_bf16_f32 v76, v10, v11
	v_cvt_pk_bf16_f32 v77, v12, v13
	v_pk_mul_f32 v[78:79], v[78:79], s[76:77] op_sel_hi:[1,0]
	v_pk_mul_f32 v[80:81], v[80:81], s[76:77] op_sel_hi:[1,0]
	v_pk_mul_f32 v[94:95], v[94:95], s[76:77] op_sel_hi:[1,0]
	v_pk_mul_f32 v[96:97], v[96:97], s[76:77] op_sel_hi:[1,0]
	v_pk_fma_f32 v[54:55], v[54:55], 0.5, v[78:79] op_sel_hi:[1,0,1]
	v_pk_fma_f32 v[56:57], v[56:57], 0.5, v[80:81] op_sel_hi:[1,0,1]
	v_pk_fma_f32 v[62:63], v[62:63], 0.5, v[94:95] op_sel_hi:[1,0,1]
	v_pk_fma_f32 v[64:65], v[64:65], 0.5, v[96:97] op_sel_hi:[1,0,1]
	v_pk_add_f32 v[78:79], v[54:55], v[62:63]
	v_pk_add_f32 v[80:81], v[56:57], v[64:65]
	v_pk_mul_f32 v[94:95], v[54:55], v[54:55]
	v_pk_mul_f32 v[96:97], v[56:57], v[56:57]
	v_pk_fma_f32 v[94:95], v[62:63], v[62:63], v[94:95]
	v_pk_fma_f32 v[96:97], v[64:65], v[64:65], v[96:97]
	v_pk_add_f32 v[78:79], v[78:79], v[80:81]
	v_pk_add_f32 v[94:95], v[94:95], v[96:97]
	v_add_f32_e32 v78, v78, v79
	v_add_f32_e32 v94, v94, v95
	v_add_f32_e32 v5, v5, v78
	v_add_f32_e32 v141, v141, v94
	v_cvt_pk_bf16_f32 v78, v54, v55
	v_cvt_pk_bf16_f32 v79, v56, v57
	v_cvt_pk_bf16_f32 v80, v62, v63
	v_cvt_pk_bf16_f32 v81, v64, v65
	v_pk_mul_f32 v[82:83], v[82:83], s[76:77] op_sel_hi:[1,0]
	v_pk_mul_f32 v[84:85], v[84:85], s[76:77] op_sel_hi:[1,0]
	v_pk_mul_f32 v[98:99], v[98:99], s[76:77] op_sel_hi:[1,0]
	v_pk_mul_f32 v[100:101], v[100:101], s[76:77] op_sel_hi:[1,0]
	v_pk_fma_f32 v[58:59], v[58:59], 0.5, v[82:83] op_sel_hi:[1,0,1]
	v_pk_fma_f32 v[60:61], v[60:61], 0.5, v[84:85] op_sel_hi:[1,0,1]
	v_pk_fma_f32 v[66:67], v[66:67], 0.5, v[98:99] op_sel_hi:[1,0,1]
	v_pk_fma_f32 v[68:69], v[68:69], 0.5, v[100:101] op_sel_hi:[1,0,1]
	v_pk_add_f32 v[82:83], v[58:59], v[66:67]
	v_pk_add_f32 v[84:85], v[60:61], v[68:69]
	v_pk_mul_f32 v[98:99], v[58:59], v[58:59]
	v_pk_mul_f32 v[100:101], v[60:61], v[60:61]
	v_pk_fma_f32 v[98:99], v[66:67], v[66:67], v[98:99]
	v_pk_fma_f32 v[100:101], v[68:69], v[68:69], v[100:101]
	v_pk_add_f32 v[82:83], v[82:83], v[84:85]
	v_pk_add_f32 v[98:99], v[98:99], v[100:101]
	v_add_f32_e32 v82, v82, v83
	v_add_f32_e32 v98, v98, v99
	v_add_f32_e32 v138, v138, v82
	v_add_f32_e32 v186, v186, v98
	v_cvt_pk_bf16_f32 v82, v58, v59
	v_cvt_pk_bf16_f32 v83, v60, v61
	v_cvt_pk_bf16_f32 v84, v66, v67
	v_cvt_pk_bf16_f32 v85, v68, v69
	v_add_u32_e32 v197, 0x80000, v226
	global_store_dwordx4 v197, v[70:73], s[18:19] offset:256
	v_add_u32_e32 v199, 0x90000, v226
	global_store_dwordx4 v199, v[74:77], s[18:19] offset:256
	v_add_u32_e32 v197, 0xa0000, v226
	global_store_dwordx4 v197, v[78:81], s[18:19] offset:256
	v_add_u32_e32 v199, 0xb0000, v226
	global_store_dwordx4 v199, v[82:85], s[18:19] offset:256
	ds_bpermute_b32 v134, v201, v2
	ds_bpermute_b32 v135, v201, v4
	ds_bpermute_b32 v136, v201, v5
	ds_bpermute_b32 v137, v201, v138
	ds_bpermute_b32 v98, v201, v139
	ds_bpermute_b32 v99, v201, v140
	ds_bpermute_b32 v100, v201, v141
	ds_bpermute_b32 v101, v201, v186
	s_waitcnt lgkmcnt(0)
	v_add_f32_e32 v2, v2, v134
	v_add_f32_e32 v4, v4, v135
	v_add_f32_e32 v5, v5, v136
	v_add_f32_e32 v138, v138, v137
	v_add_f32_e32 v139, v139, v98
	v_add_f32_e32 v140, v140, v99
	v_add_f32_e32 v141, v141, v100
	v_add_f32_e32 v186, v186, v101
	ds_bpermute_b32 v134, v203, v2
	ds_bpermute_b32 v135, v203, v4
	ds_bpermute_b32 v136, v203, v5
	ds_bpermute_b32 v137, v203, v138
	ds_bpermute_b32 v98, v203, v139
	ds_bpermute_b32 v99, v203, v140
	ds_bpermute_b32 v100, v203, v141
	ds_bpermute_b32 v101, v203, v186
	s_waitcnt lgkmcnt(0)
	v_add_f32_e32 v2, v2, v134
	v_add_f32_e32 v4, v4, v135
	v_add_f32_e32 v5, v5, v136
	v_add_f32_e32 v138, v138, v137
	v_add_f32_e32 v139, v139, v98
	v_add_f32_e32 v140, v140, v99
	v_add_f32_e32 v141, v141, v100
	v_add_f32_e32 v186, v186, v101
	v_cmp_eq_u32_e32 vcc, 1, v191
	s_nop 1
	v_cndmask_b32_e32 v2, v2, v4, vcc
	v_cndmask_b32_e32 v139, v139, v140, vcc
	v_cmp_eq_u32_e32 vcc, 2, v191
	s_nop 1
	v_cndmask_b32_e32 v2, v2, v5, vcc
	v_cndmask_b32_e32 v139, v139, v141, vcc
	v_cmp_eq_u32_e32 vcc, 3, v191
	s_nop 1
	v_cndmask_b32_e32 v2, v2, v138, vcc
	v_cndmask_b32_e32 v139, v139, v186, vcc
	global_atomic_add_f32 v227, v2, s[16:17] offset:1024
	global_atomic_add_f32 v227, v139, s[16:17] offset:1028
	s_branch .LBB0_1106

.LBB0_1082:
	s_and_b64 vcc, exec, s[0:1]
	s_cbranch_vccz .LBB0_1106
	s_cmp_eq_u32 s84, 0xff
	s_cbranch_scc1 .Lxfast
	s_cmp_lt_i32 s4, 32
	s_cselect_b32 s0, 0, 0xffffe000
	s_waitcnt lgkmcnt(0)
	v_add_u32_e32 v4, s0, v180
	v_ashrrev_i32_e32 v5, 31, v4
	s_cselect_b32 s1, s56, s58
	s_cselect_b32 s0, s43, s57
	v_lshlrev_b64 v[4:5], 13, v[4:5]
	v_lshl_add_u64 v[4:5], s[0:1], 0, v[4:5]
	v_ashrrev_i32_e32 v179, 31, v178
	s_bitcmp0_b32 s84, 0
	v_lshl_add_u64 v[4:5], v[178:179], 2, v[4:5]
	s_cbranch_scc1 .LBB0_1088
	global_load_dwordx4 v[134:137], v[4:5], off offset:16
	global_load_dwordx4 v[138:141], v[4:5], off
	v_ashrrev_i32_e32 v181, 31, v180
	v_cmp_lt_i32_e32 vcc, v234, v230
	s_waitcnt vmcnt(0)
	v_pk_mul_f32 v[136:137], v[136:137], s[76:77] op_sel_hi:[1,0]
	v_pk_mul_f32 v[138:139], v[138:139], s[76:77] op_sel_hi:[1,0]
	v_pk_mul_f32 v[134:135], v[134:135], s[76:77] op_sel_hi:[1,0]
	v_pk_mul_f32 v[140:141], v[140:141], s[76:77] op_sel_hi:[1,0]
	v_pk_fma_f32 v[138:139], v[126:127], 0.5, v[138:139] op_sel_hi:[1,0,1]
	v_pk_fma_f32 v[144:145], v[132:133], 0.5, v[136:137] op_sel_hi:[1,0,1]
	v_pk_fma_f32 v[146:147], v[130:131], 0.5, v[134:135] op_sel_hi:[1,0,1]
	v_pk_fma_f32 v[140:141], v[128:129], 0.5, v[140:141] op_sel_hi:[1,0,1]
	v_mul_f32_e32 v134, v146, v146
	v_mul_f32_e32 v136, v147, v147
	v_mul_f32_e32 v148, v144, v144
	v_mul_f32_e32 v150, v145, v145
	v_pk_mul_f32 v[152:153], v[138:139], v[138:139]
	v_pk_add_f32 v[154:155], v[138:139], v[138:139] op_sel_hi:[0,1]
	v_mov_b32_e32 v135, v146
	v_mov_b32_e32 v137, v147
	v_mov_b32_e32 v151, v145
	v_mov_b32_e32 v149, v144
	v_mul_f32_e32 v2, v141, v141
	v_mov_b32_e32 v153, v155
	v_pk_mov_b32 v[154:155], v[138:139], v[140:141] op_sel:[1,0]
	v_pk_add_f32 v[134:135], v[134:135], v[136:137]
	v_pk_add_f32 v[136:137], v[150:151], v[148:149]
	v_pk_fma_f32 v[142:143], v[140:141], v[140:141], v[2:3] op_sel_hi:[1,1,0]
	v_pk_mul_f32 v[156:157], v[138:139], v[154:155] op_sel:[1,0] op_sel_hi:[0,1]
	v_pk_add_f32 v[154:155], v[140:141], v[154:155]
	v_pk_add_f32 v[134:135], v[134:135], v[136:137]
	v_cvt_pk_bf16_f32 v137, v140, v141
	v_lshlrev_b64 v[140:141], 12, v[180:181]
	v_mov_b32_e32 v157, v155
	v_lshl_add_u64 v[140:141], s[18:19], 0, v[140:141]
	v_pk_add_f32 v[152:153], v[152:153], v[156:157]
	v_mov_b32_e32 v143, v3
	v_cvt_pk_bf16_f32 v136, v138, v139
	v_cvt_pk_bf16_f32 v138, v146, v147
	v_cvt_pk_bf16_f32 v139, v144, v145
	v_lshl_add_u64 v[144:145], v[178:179], 1, v[140:141]
	v_pk_add_f32 v[142:143], v[152:153], v[142:143]
	global_store_dwordx4 v[144:145], v[136:139], off
	v_pk_add_f32 v[134:135], v[134:135], v[142:143]
	global_load_dwordx4 v[136:139], v[4:5], off offset:528
	global_load_dwordx4 v[140:143], v[4:5], off offset:512
	v_cndmask_b32_e32 v2, v228, v234, vcc
	v_lshlrev_b32_e32 v2, 2, v2
	v_cmp_lt_i32_e32 vcc, v195, v230
	s_waitcnt vmcnt(1)
	v_pk_mul_f32 v[136:137], v[136:137], s[76:77] op_sel_hi:[1,0]
	s_waitcnt vmcnt(0)
	v_pk_mul_f32 v[142:143], v[142:143], s[76:77] op_sel_hi:[1,0]
	v_pk_mul_f32 v[140:141], v[140:141], s[76:77] op_sel_hi:[1,0]
	v_pk_fma_f32 v[142:143], v[96:97], 0.5, v[142:143] op_sel_hi:[1,0,1]
	v_pk_fma_f32 v[140:141], v[94:95], 0.5, v[140:141] op_sel_hi:[1,0,1]
	v_mul_f32_e32 v150, v142, v142
	v_mul_f32_e32 v146, v140, v140
	v_mul_f32_e32 v148, v141, v141
	v_mul_f32_e32 v152, v143, v143
	v_mov_b32_e32 v147, v140
	v_mov_b32_e32 v149, v141
	v_mov_b32_e32 v153, v143
	v_mov_b32_e32 v151, v142
	v_pk_add_f32 v[146:147], v[146:147], v[148:149]
	v_pk_add_f32 v[148:149], v[152:153], v[150:151]
	v_pk_mul_f32 v[138:139], v[138:139], s[76:77] op_sel_hi:[1,0]
	v_pk_fma_f32 v[150:151], v[98:99], 0.5, v[136:137] op_sel_hi:[1,0,1]
	v_pk_add_f32 v[146:147], v[146:147], v[148:149]
	v_pk_fma_f32 v[148:149], v[100:101], 0.5, v[138:139] op_sel_hi:[1,0,1]
	v_mul_f32_e32 v136, v150, v150
	v_mul_f32_e32 v138, v151, v151
	v_mov_b32_e32 v137, v150
	v_mov_b32_e32 v139, v151
	v_pk_add_f32 v[136:137], v[136:137], v[138:139]
	v_mul_f32_e32 v138, v148, v148
	v_mul_f32_e32 v152, v149, v149
	v_mov_b32_e32 v153, v149
	v_mov_b32_e32 v139, v148
	v_pk_add_f32 v[138:139], v[152:153], v[138:139]
	v_pk_add_f32 v[134:135], v[134:135], v[146:147]
	v_pk_add_f32 v[136:137], v[136:137], v[138:139]
	v_cvt_pk_bf16_f32 v140, v140, v141
	v_pk_add_f32 v[134:135], v[134:135], v[136:137]
	ds_bpermute_b32 v137, v2, v135
	ds_bpermute_b32 v136, v2, v134
	v_cvt_pk_bf16_f32 v141, v142, v143
	v_cvt_pk_bf16_f32 v142, v150, v151
	v_cvt_pk_bf16_f32 v143, v148, v149
	global_store_dwordx4 v[144:145], v[140:143], off offset:256
	s_waitcnt lgkmcnt(0)
	v_pk_add_f32 v[134:135], v[134:135], v[136:137]
	v_cndmask_b32_e32 v140, v228, v195, vcc
	v_lshlrev_b32_e32 v140, 2, v140
	ds_bpermute_b32 v137, v140, v135
	ds_bpermute_b32 v136, v140, v134
	v_cmp_eq_u32_e32 vcc, 0, v191
	s_waitcnt lgkmcnt(0)
	v_pk_add_f32 v[134:135], v[134:135], v[136:137]
	s_nop 0
	v_cndmask_b32_e32 v137, 0, v135, vcc
	v_cndmask_b32_e32 v136, 0, v134, vcc
	s_bitcmp0_b32 s84, 1
	s_cbranch_scc0 .LBB0_1089
	s_branch .LBB0_1090
